# pool item: weight-staging loads and the six row-prefetch loads per chunk issued together (each was load plus full wait)
# speedup vs baseline: 1.0030x; 1.0021x over previous
.LBB0_625:
	s_mov_b64 s[12:13], s[0:1]
	s_load_dwordx2 s[10:11], s[12:13], 0x30
	s_load_dwordx4 s[40:43], s[12:13], 0xc8
	v_mov_b32_e32 v60, v236
	v_readlane_b32 s4, v255, 50
	v_lshlrev_b32_e32 v86, 4, v60
	s_waitcnt lgkmcnt(0)
	s_add_u32 s16, s42, s92
	s_addc_u32 s17, s43, s93
	v_and_b32_e32 v174, 0x70, v86
	s_waitcnt vmcnt(5)
	v_ashrrev_i32_e32 v8, 3, v60
	v_lshl_add_u64 v[0:1], s[16:17], 0, v[174:175]
	s_mov_b64 s[16:17], 0xefbe000
	v_ashrrev_i32_e32 v9, 31, v8
	v_lshl_add_u64 v[4:5], v[0:1], 0, s[16:17]
	v_lshlrev_b64 v[0:1], 7, v[8:9]
	v_lshl_add_u64 v[0:1], v[4:5], 0, v[0:1]
	global_load_dwordx4 v[196:199], v[0:1], off
	v_add_u32_e32 v6, s4, v174
	v_mad_u64_u32 v[212:213], s[16:17], v8, s97, v[6:7]
	v_add_u32_e32 v87, 0x200, v60
	v_add_u32_e32 v88, 0x400, v60
	v_add_u32_e32 v89, 0x600, v60
	v_ashrrev_i32_e32 v83, 6, v60
	v_cmp_gt_i32_e32 vcc, 64, v60
	v_readfirstlane_b32 s21, v83
	v_ashrrev_i32_e32 v8, 3, v87
	v_ashrrev_i32_e32 v9, 31, v8
	v_lshlrev_b64 v[0:1], 7, v[8:9]
	v_lshl_add_u64 v[0:1], v[4:5], 0, v[0:1]
	global_load_dwordx4 v[200:203], v[0:1], off
	v_mad_u64_u32 v[214:215], s[16:17], v8, s97, v[6:7]
	v_ashrrev_i32_e32 v8, 3, v88
	v_ashrrev_i32_e32 v9, 31, v8
	v_lshlrev_b64 v[0:1], 7, v[8:9]
	v_lshl_add_u64 v[0:1], v[4:5], 0, v[0:1]
	global_load_dwordx4 v[204:207], v[0:1], off
	v_mad_u64_u32 v[216:217], s[16:17], v8, s97, v[6:7]
	v_ashrrev_i32_e32 v8, 3, v89
	v_ashrrev_i32_e32 v9, 31, v8
	v_lshlrev_b64 v[0:1], 7, v[8:9]
	v_lshl_add_u64 v[0:1], v[4:5], 0, v[0:1]
	global_load_dwordx4 v[208:211], v[0:1], off
	v_mad_u64_u32 v[218:219], s[16:17], v8, s97, v[6:7]
	s_waitcnt vmcnt(0)
	ds_write_b128 v212, v[196:199]
	ds_write_b128 v214, v[200:203]
	ds_write_b128 v216, v[204:207]
	ds_write_b128 v218, v[208:211]
	s_and_saveexec_b64 s[16:17], vcc
	s_cbranch_execz .LBB0_627
	s_load_dwordx2 s[12:13], s[12:13], 0x88
	s_lshl_b64 s[22:23], s[84:85], 2
	v_lshl_add_u32 v0, v60, 4, 0
	v_ashrrev_i32_e32 v61, 31, v60
	v_add_u32_e32 v4, 0x25400, v0
	s_waitcnt lgkmcnt(0)
	s_add_u32 s12, s12, s22
	s_addc_u32 s13, s13, s23
	v_lshl_add_u64 v[0:1], v[60:61], 4, s[12:13]
	global_load_dwordx4 v[0:3], v[0:1], off
	s_waitcnt vmcnt(0)
	ds_write_b128 v4, v[0:3]

.LBB0_643:
	s_or_b64 exec, exec, s[10:11]
	s_lshl_b32 s4, s24, 7
	s_add_i32 s12, s4, -15
	v_lshlrev_b32_e32 v0, 2, v60
	v_add_u32_e32 v1, s12, v83
	s_movk_i32 s10, 0xbc0
	v_and_b32_e32 v2, 0xfc, v0
	v_cmp_gt_i32_e64 s[22:23], s10, v60
	v_cmp_lt_i32_e64 s[24:25], -1, v1
	s_and_b64 s[16:17], s[22:23], s[24:25]
	v_mov_b32_e32 v0, 0
	v_lshlrev_b32_e32 v32, 1, v2
	v_mov_b32_e32 v4, 0
	v_mov_b32_e32 v5, 0
	v_mov_b32_e32 v6, 0
	v_mov_b32_e32 v7, 0
	v_mov_b32_e32 v184, 0
	v_mov_b32_e32 v185, 0
	v_mov_b32_e32 v186, 0
	v_mov_b32_e32 v187, 0
	v_mov_b32_e32 v188, 0
	v_mov_b32_e32 v189, 0
	v_mov_b32_e32 v190, 0
	v_mov_b32_e32 v191, 0
	v_mov_b32_e32 v192, 0
	v_mov_b32_e32 v193, 0
	v_mov_b32_e32 v194, 0
	v_mov_b32_e32 v195, 0
	s_and_saveexec_b64 s[10:11], s[16:17]
	s_cbranch_execz .LBB0_645
	v_add_u32_e32 v1, s50, v1
	v_mov_b64_e32 v[2:3], s[48:49]
	v_mad_u64_u32 v[2:3], s[16:17], v1, s18, v[2:3]
	v_mov_b32_e32 v33, v175
	v_lshl_add_u64 v[2:3], v[2:3], 0, v[32:33]
	global_load_dwordx2 v[184:185], v[2:3], off offset:1024
.LBB0_645:
	s_or_b64 exec, exec, s[10:11]
	v_ashrrev_i32_e32 v44, 6, v87
	v_add_u32_e32 v8, s12, v44
	s_movk_i32 s10, 0x9c0
	v_cmp_gt_i32_e64 s[24:25], s10, v60
	v_cmp_lt_i32_e64 s[26:27], -1, v8
	s_and_b64 s[16:17], s[24:25], s[26:27]
	v_mov_b32_e32 v1, 0
	v_mov_b32_e32 v2, 0
	v_mov_b32_e32 v3, 0
	s_and_saveexec_b64 s[10:11], s[16:17]
	s_cbranch_execz .LBB0_647
	v_add_u32_e32 v2, s50, v8
	v_mov_b64_e32 v[0:1], s[48:49]
	v_mad_u64_u32 v[0:1], s[16:17], v2, s18, v[0:1]
	v_mov_b32_e32 v33, v175
	v_lshl_add_u64 v[0:1], v[0:1], 0, v[32:33]
	global_load_dwordx2 v[186:187], v[0:1], off offset:1024
.LBB0_647:
	s_or_b64 exec, exec, s[10:11]
	v_ashrrev_i32_e32 v45, 6, v88
	v_add_u32_e32 v9, s12, v45
	s_movk_i32 s10, 0x7c0
	v_cmp_gt_i32_e64 s[26:27], s10, v60
	v_cmp_lt_i32_e64 s[28:29], -1, v9
	s_and_b64 s[16:17], s[26:27], s[28:29]
	v_mov_b32_e32 v8, 0
	v_mov_b32_e32 v12, 0
	v_mov_b32_e32 v13, 0
	v_mov_b32_e32 v14, 0
	v_mov_b32_e32 v15, 0
	s_and_saveexec_b64 s[10:11], s[16:17]
	s_cbranch_execz .LBB0_649
	v_add_u32_e32 v9, s50, v9
	v_mov_b64_e32 v[10:11], s[48:49]
	v_mad_u64_u32 v[10:11], s[16:17], v9, s18, v[10:11]
	v_mov_b32_e32 v33, v175
	v_lshl_add_u64 v[10:11], v[10:11], 0, v[32:33]
	global_load_dwordx2 v[188:189], v[10:11], off offset:1024
.LBB0_649:
	s_or_b64 exec, exec, s[10:11]
	v_ashrrev_i32_e32 v46, 6, v89
	v_add_u32_e32 v16, s12, v46
	s_movk_i32 s10, 0x5c0
	v_cmp_gt_i32_e64 s[28:29], s10, v60
	v_cmp_lt_i32_e64 s[30:31], -1, v16
	s_and_b64 s[16:17], s[28:29], s[30:31]
	v_mov_b32_e32 v9, 0
	v_mov_b32_e32 v10, 0
	v_mov_b32_e32 v11, 0
	s_and_saveexec_b64 s[10:11], s[16:17]
	s_cbranch_execz .LBB0_651
	v_add_u32_e32 v10, s50, v16
	v_mov_b64_e32 v[8:9], s[48:49]
	v_mad_u64_u32 v[8:9], s[16:17], v10, s18, v[8:9]
	v_mov_b32_e32 v33, v175
	v_lshl_add_u64 v[8:9], v[8:9], 0, v[32:33]
	global_load_dwordx2 v[190:191], v[8:9], off offset:1024
.LBB0_651:
	s_or_b64 exec, exec, s[10:11]
	v_add_u32_e32 v24, 0x800, v60
	v_ashrrev_i32_e32 v47, 6, v24
	v_add_u32_e32 v17, s12, v47
	v_cmp_lt_i32_e64 s[30:31], -1, v17
	s_and_b64 s[16:17], vcc, s[30:31]
	v_mov_b32_e32 v16, 0
	v_mov_b32_e32 v20, 0
	v_mov_b32_e32 v21, 0
	v_mov_b32_e32 v22, 0
	v_mov_b32_e32 v23, 0
	s_and_saveexec_b64 s[10:11], s[16:17]
	s_cbranch_execz .LBB0_653
	v_add_u32_e32 v17, s50, v17
	v_mov_b64_e32 v[18:19], s[48:49]
	v_mad_u64_u32 v[18:19], s[16:17], v17, s18, v[18:19]
	v_mov_b32_e32 v33, v175
	v_lshl_add_u64 v[18:19], v[18:19], 0, v[32:33]
	global_load_dwordx2 v[192:193], v[18:19], off offset:1024
.LBB0_653:
	s_or_b64 exec, exec, s[10:11]
	v_add_u32_e32 v25, 0xa00, v60
	v_ashrrev_i32_e32 v48, 6, v25
	v_add_u32_e32 v26, s12, v48
	s_movk_i32 s10, 0x1c0
	v_cmp_gt_i32_e64 s[30:31], s10, v60
	v_cmp_lt_i32_e64 s[34:35], -1, v26
	s_and_b64 s[12:13], s[30:31], s[34:35]
	v_mov_b32_e32 v17, 0
	v_mov_b32_e32 v18, 0
	v_mov_b32_e32 v19, 0
	s_and_saveexec_b64 s[10:11], s[12:13]
	s_cbranch_execz .LBB0_655
	v_add_u32_e32 v18, s50, v26
	v_mov_b64_e32 v[16:17], s[48:49]
	v_mad_u64_u32 v[16:17], s[12:13], v18, s18, v[16:17]
	v_mov_b32_e32 v33, v175
	v_lshl_add_u64 v[16:17], v[16:17], 0, v[32:33]
	global_load_dwordx2 v[194:195], v[16:17], off offset:1024
.LBB0_655:
	s_or_b64 exec, exec, s[10:11]
	s_waitcnt vmcnt(0)
	v_lshlrev_b32_e32 v4, 16, v184
	v_and_b32_e32 v5, 0xffff0000, v184
	v_lshlrev_b32_e32 v6, 16, v185
	v_and_b32_e32 v7, 0xffff0000, v185
	v_lshlrev_b32_e32 v0, 16, v186
	v_and_b32_e32 v1, 0xffff0000, v186
	v_lshlrev_b32_e32 v2, 16, v187
	v_and_b32_e32 v3, 0xffff0000, v187
	v_lshlrev_b32_e32 v12, 16, v188
	v_and_b32_e32 v13, 0xffff0000, v188
	v_lshlrev_b32_e32 v14, 16, v189
	v_and_b32_e32 v15, 0xffff0000, v189
	v_lshlrev_b32_e32 v8, 16, v190
	v_and_b32_e32 v9, 0xffff0000, v190
	v_lshlrev_b32_e32 v10, 16, v191
	v_and_b32_e32 v11, 0xffff0000, v191
	v_lshlrev_b32_e32 v20, 16, v192
	v_and_b32_e32 v21, 0xffff0000, v192
	v_lshlrev_b32_e32 v22, 16, v193
	v_and_b32_e32 v23, 0xffff0000, v193
	v_lshlrev_b32_e32 v16, 16, v194
	v_and_b32_e32 v17, 0xffff0000, v194
	v_lshlrev_b32_e32 v18, 16, v195
	v_and_b32_e32 v19, 0xffff0000, v195
	v_add_u32_e32 v35, 0, v86
	s_and_saveexec_b64 s[10:11], s[22:23]
	ds_write_b128 v35, v[4:7]
	s_or_b64 exec, exec, s[10:11]
	v_lshlrev_b32_e32 v4, 4, v87
	v_add_u32_e32 v36, 0, v4
	s_and_saveexec_b64 s[10:11], s[24:25]
	ds_write_b128 v36, v[0:3]
	s_or_b64 exec, exec, s[10:11]
	v_lshlrev_b32_e32 v0, 4, v88
	v_add_u32_e32 v37, 0, v0
	s_and_saveexec_b64 s[10:11], s[26:27]
	ds_write_b128 v37, v[12:15]
	s_or_b64 exec, exec, s[10:11]
	v_lshlrev_b32_e32 v0, 4, v89
	v_add_u32_e32 v38, 0, v0
	s_and_saveexec_b64 s[10:11], s[28:29]
	ds_write_b128 v38, v[8:11]
	s_or_b64 exec, exec, s[10:11]
	v_lshlrev_b32_e32 v0, 4, v24
	v_add_u32_e32 v39, 0, v0
	s_and_saveexec_b64 s[10:11], vcc
	ds_write_b128 v39, v[20:23]
	s_or_b64 exec, exec, s[10:11]
	v_lshlrev_b32_e32 v0, 4, v25
	v_add_u32_e32 v40, 0, v0
	s_and_saveexec_b64 s[10:11], s[30:31]
	ds_write_b128 v40, v[16:19]
	s_or_b64 exec, exec, s[10:11]
	s_or_b32 s12, s4, 17
	v_add_u32_e32 v1, s12, v83
	v_cmp_lt_i32_e64 s[34:35], -1, v1
	s_and_b64 s[16:17], s[22:23], s[34:35]
	v_mov_b32_e32 v0, 0
	v_mov_b32_e32 v4, 0
	v_mov_b32_e32 v5, 0
	v_mov_b32_e32 v6, 0
	v_mov_b32_e32 v7, 0
	s_waitcnt lgkmcnt(0)
	s_barrier
	v_mov_b32_e32 v184, 0
	v_mov_b32_e32 v185, 0
	v_mov_b32_e32 v186, 0
	v_mov_b32_e32 v187, 0
	v_mov_b32_e32 v188, 0
	v_mov_b32_e32 v189, 0
	v_mov_b32_e32 v190, 0
	v_mov_b32_e32 v191, 0
	v_mov_b32_e32 v192, 0
	v_mov_b32_e32 v193, 0
	v_mov_b32_e32 v194, 0
	v_mov_b32_e32 v195, 0
	s_and_saveexec_b64 s[10:11], s[16:17]
	s_cbranch_execz .LBB0_669
	v_add_u32_e32 v1, s50, v1
	v_mov_b64_e32 v[2:3], s[48:49]
	v_mad_u64_u32 v[2:3], s[16:17], v1, s18, v[2:3]
	v_mov_b32_e32 v33, v175
	v_lshl_add_u64 v[2:3], v[2:3], 0, v[32:33]
	global_load_dwordx2 v[184:185], v[2:3], off offset:1024
.LBB0_669:
	s_or_b64 exec, exec, s[10:11]
	v_add_u32_e32 v8, s12, v44
	v_cmp_lt_i32_e64 s[34:35], -1, v8
	s_and_b64 s[16:17], s[24:25], s[34:35]
	v_mov_b32_e32 v1, 0
	v_mov_b32_e32 v2, 0
	v_mov_b32_e32 v3, 0
	s_and_saveexec_b64 s[10:11], s[16:17]
	s_cbranch_execz .LBB0_671
	v_add_u32_e32 v2, s50, v8
	v_mov_b64_e32 v[0:1], s[48:49]
	v_mad_u64_u32 v[0:1], s[16:17], v2, s18, v[0:1]
	v_mov_b32_e32 v33, v175
	v_lshl_add_u64 v[0:1], v[0:1], 0, v[32:33]
	global_load_dwordx2 v[186:187], v[0:1], off offset:1024
.LBB0_671:
	s_or_b64 exec, exec, s[10:11]
	v_add_u32_e32 v9, s12, v45
	v_cmp_lt_i32_e64 s[34:35], -1, v9
	s_and_b64 s[16:17], s[26:27], s[34:35]
	v_mov_b32_e32 v8, 0
	v_mov_b32_e32 v12, 0
	v_mov_b32_e32 v13, 0
	v_mov_b32_e32 v14, 0
	v_mov_b32_e32 v15, 0
	s_and_saveexec_b64 s[10:11], s[16:17]
	s_cbranch_execz .LBB0_673
	v_add_u32_e32 v9, s50, v9
	v_mov_b64_e32 v[10:11], s[48:49]
	v_mad_u64_u32 v[10:11], s[16:17], v9, s18, v[10:11]
	v_mov_b32_e32 v33, v175
	v_lshl_add_u64 v[10:11], v[10:11], 0, v[32:33]
	global_load_dwordx2 v[188:189], v[10:11], off offset:1024
.LBB0_673:
	s_or_b64 exec, exec, s[10:11]
	v_add_u32_e32 v16, s12, v46
	v_cmp_lt_i32_e64 s[34:35], -1, v16
	s_and_b64 s[16:17], s[28:29], s[34:35]
	v_mov_b32_e32 v9, 0
	v_mov_b32_e32 v10, 0
	v_mov_b32_e32 v11, 0
	s_and_saveexec_b64 s[10:11], s[16:17]
	s_cbranch_execz .LBB0_675
	v_add_u32_e32 v10, s50, v16
	v_mov_b64_e32 v[8:9], s[48:49]
	v_mad_u64_u32 v[8:9], s[16:17], v10, s18, v[8:9]
	v_mov_b32_e32 v33, v175
	v_lshl_add_u64 v[8:9], v[8:9], 0, v[32:33]
	global_load_dwordx2 v[190:191], v[8:9], off offset:1024
.LBB0_675:
	s_or_b64 exec, exec, s[10:11]
	v_add_u32_e32 v17, s12, v47
	v_cmp_lt_i32_e64 s[34:35], -1, v17
	s_and_b64 s[16:17], vcc, s[34:35]
	v_mov_b32_e32 v16, 0
	v_mov_b32_e32 v20, 0
	v_mov_b32_e32 v21, 0
	v_mov_b32_e32 v22, 0
	v_mov_b32_e32 v23, 0
	s_and_saveexec_b64 s[10:11], s[16:17]
	s_cbranch_execz .LBB0_677
	v_add_u32_e32 v17, s50, v17
	v_mov_b64_e32 v[18:19], s[48:49]
	v_mad_u64_u32 v[18:19], s[16:17], v17, s18, v[18:19]
	v_mov_b32_e32 v33, v175
	v_lshl_add_u64 v[18:19], v[18:19], 0, v[32:33]
	global_load_dwordx2 v[192:193], v[18:19], off offset:1024
.LBB0_677:
	s_or_b64 exec, exec, s[10:11]
	v_add_u32_e32 v24, s12, v48
	v_cmp_lt_i32_e64 s[34:35], -1, v24
	s_and_b64 s[12:13], s[30:31], s[34:35]
	v_mov_b32_e32 v17, 0
	v_mov_b32_e32 v18, 0
	v_mov_b32_e32 v19, 0
	s_and_saveexec_b64 s[10:11], s[12:13]
	s_cbranch_execz .LBB0_679
	v_add_u32_e32 v18, s50, v24
	v_mov_b64_e32 v[16:17], s[48:49]
	v_mad_u64_u32 v[16:17], s[12:13], v18, s18, v[16:17]
	v_mov_b32_e32 v33, v175
	v_lshl_add_u64 v[16:17], v[16:17], 0, v[32:33]
	global_load_dwordx2 v[194:195], v[16:17], off offset:1024
.LBB0_679:
	s_or_b64 exec, exec, s[10:11]
	s_waitcnt vmcnt(0)
	v_lshlrev_b32_e32 v4, 16, v184
	v_and_b32_e32 v5, 0xffff0000, v184
	v_lshlrev_b32_e32 v6, 16, v185
	v_and_b32_e32 v7, 0xffff0000, v185
	v_lshlrev_b32_e32 v0, 16, v186
	v_and_b32_e32 v1, 0xffff0000, v186
	v_lshlrev_b32_e32 v2, 16, v187
	v_and_b32_e32 v3, 0xffff0000, v187
	v_lshlrev_b32_e32 v12, 16, v188
	v_and_b32_e32 v13, 0xffff0000, v188
	v_lshlrev_b32_e32 v14, 16, v189
	v_and_b32_e32 v15, 0xffff0000, v189
	v_lshlrev_b32_e32 v8, 16, v190
	v_and_b32_e32 v9, 0xffff0000, v190
	v_lshlrev_b32_e32 v10, 16, v191
	v_and_b32_e32 v11, 0xffff0000, v191
	v_lshlrev_b32_e32 v20, 16, v192
	v_and_b32_e32 v21, 0xffff0000, v192
	v_lshlrev_b32_e32 v22, 16, v193
	v_and_b32_e32 v23, 0xffff0000, v193
	v_lshlrev_b32_e32 v16, 16, v194
	v_and_b32_e32 v17, 0xffff0000, v194
	v_lshlrev_b32_e32 v18, 16, v195
	v_and_b32_e32 v19, 0xffff0000, v195
	v_lshl_add_u32 v24, v83, 12, 0
	v_add_u32_e32 v43, v24, v174
	ds_read_b128 v[50:53], v43
	ds_read_b128 v[54:57], v43 offset:1024
	ds_read_b128 v[62:65], v43 offset:2048
	ds_read_b128 v[66:69], v43 offset:3072
	ds_read_b128 v[70:73], v43 offset:4096
	ds_read_b128 v[74:77], v43 offset:5120
	ds_read_b128 v[78:81], v43 offset:6144
	ds_read_b128 v[86:89], v43 offset:7168
	ds_read_b128 v[90:93], v43 offset:8192
	ds_read_b128 v[94:97], v43 offset:9216
	ds_read_b128 v[98:101], v43 offset:10240
	ds_read_b128 v[102:105], v43 offset:11264
	ds_read_b128 v[106:109], v43 offset:16384
	ds_read_b128 v[28:31], v43 offset:17408
	ds_read_b128 v[24:27], v43 offset:18432
	ds_read_b128 v[110:113], v43 offset:12288
	ds_read_b128 v[114:117], v43 offset:13312
	ds_read_b128 v[118:121], v43 offset:14336
	ds_read_b128 v[122:125], v43 offset:15360
	s_waitcnt lgkmcnt(14)
	v_pk_add_f32 v[50:51], v[50:51], v[54:55]
	v_pk_add_f32 v[52:53], v[52:53], v[56:57]
	v_cmp_gt_u32_e64 s[36:37], 16, v85
	v_cmp_lt_u32_e64 s[38:39], 31, v85
	s_waitcnt lgkmcnt(0)
	v_pk_add_f32 v[138:139], v[118:119], v[122:123]
	v_pk_add_f32 v[118:119], v[114:115], v[118:119]
	v_pk_add_f32 v[114:115], v[110:111], v[114:115]
	v_pk_add_f32 v[110:111], v[102:103], v[110:111]
	v_pk_add_f32 v[102:103], v[98:99], v[102:103]
	v_pk_add_f32 v[98:99], v[94:95], v[98:99]
	v_pk_add_f32 v[94:95], v[90:91], v[94:95]
	v_pk_add_f32 v[90:91], v[86:87], v[90:91]
	v_pk_add_f32 v[86:87], v[78:79], v[86:87]
	v_pk_add_f32 v[78:79], v[74:75], v[78:79]
	v_pk_add_f32 v[74:75], v[70:71], v[74:75]
	v_pk_add_f32 v[70:71], v[66:67], v[70:71]
	v_pk_add_f32 v[66:67], v[62:63], v[66:67]
	v_pk_add_f32 v[136:137], v[120:121], v[124:125]
	v_pk_add_f32 v[120:121], v[116:117], v[120:121]
	v_pk_add_f32 v[116:117], v[112:113], v[116:117]
	v_pk_add_f32 v[112:113], v[104:105], v[112:113]
	v_pk_add_f32 v[104:105], v[100:101], v[104:105]
	v_pk_add_f32 v[100:101], v[96:97], v[100:101]
	v_pk_add_f32 v[96:97], v[92:93], v[96:97]
	v_pk_add_f32 v[92:93], v[88:89], v[92:93]
	v_pk_add_f32 v[88:89], v[80:81], v[88:89]
	v_pk_add_f32 v[80:81], v[76:77], v[80:81]
	v_pk_add_f32 v[76:77], v[72:73], v[76:77]
	v_pk_add_f32 v[72:73], v[68:69], v[72:73]
	v_pk_add_f32 v[68:69], v[64:65], v[68:69]
	v_pk_add_f32 v[150:151], v[114:115], v[138:139]
	v_pk_add_f32 v[114:115], v[102:103], v[114:115]
	v_pk_add_f32 v[102:103], v[94:95], v[102:103]
	v_pk_add_f32 v[94:95], v[86:87], v[94:95]
	v_pk_add_f32 v[86:87], v[74:75], v[86:87]
	v_pk_add_f32 v[50:51], v[50:51], v[66:67]
	v_pk_add_f32 v[132:133], v[124:125], v[108:109]
	v_pk_add_f32 v[64:65], v[56:57], v[64:65]
	v_pk_add_f32 v[148:149], v[116:117], v[136:137]
	v_pk_add_f32 v[116:117], v[104:105], v[116:117]
	v_pk_add_f32 v[104:105], v[96:97], v[104:105]
	v_pk_add_f32 v[96:97], v[88:89], v[96:97]
	v_pk_add_f32 v[88:89], v[76:77], v[88:89]
	v_pk_add_f32 v[52:53], v[52:53], v[68:69]
	v_cndmask_b32_e64 v42, v151, v139, s[36:37]
	v_pk_add_f32 v[102:103], v[102:103], v[150:151]
	v_pk_add_f32 v[50:51], v[50:51], v[86:87]
	s_or_b32 s10, s4, 1
	v_pk_add_f32 v[144:145], v[120:121], v[132:133]
	v_pk_add_f32 v[120:121], v[112:113], v[120:121]
	v_pk_add_f32 v[112:113], v[100:101], v[112:113]
	v_pk_add_f32 v[100:101], v[92:93], v[100:101]
	v_pk_add_f32 v[92:93], v[80:81], v[92:93]
	v_pk_add_f32 v[80:81], v[72:73], v[80:81]
	v_pk_add_f32 v[64:65], v[64:65], v[72:73]
	v_cndmask_b32_e64 v33, v149, v137, s[36:37]
	v_pk_add_f32 v[72:73], v[104:105], v[148:149]
	v_pk_add_f32 v[52:53], v[52:53], v[88:89]
	v_cndmask_b32_e64 v42, v42, v103, s[38:39]
	v_pk_add_f32 v[50:51], v[50:51], v[102:103]
	v_cmp_eq_u32_e64 s[34:35], 3, v61
	v_cndmask_b32_e64 v33, v33, v73, s[38:39]
	v_pk_add_f32 v[52:53], v[52:53], v[72:73]
	v_cndmask_b32_e64 v51, v42, v51, s[34:35]
	v_add_u32_e32 v42, s10, v82
	v_cndmask_b32_e64 v53, v33, v53, s[34:35]
	v_cvt_f32_i32_e32 v33, v42
	v_cndmask_b32_e64 v41, v148, v136, s[36:37]
	v_cndmask_b32_e64 v41, v41, v72, s[38:39]
	v_pk_add_f32 v[58:59], v[30:31], v[26:27]
	v_cndmask_b32_e64 v52, v41, v52, s[34:35]
	v_max_f32_e32 v41, v84, v84
	v_pk_add_f32 v[62:63], v[54:55], v[62:63]
	v_pk_add_f32 v[54:55], v[132:133], v[58:59]
	v_pk_add_f32 v[76:77], v[68:69], v[76:77]
	v_cndmask_b32_e64 v49, v150, v138, s[36:37]
	v_cndmask_b32_e64 v132, v144, v132, s[36:37]
	v_pk_add_f32 v[68:69], v[112:113], v[144:145]
	v_pk_add_f32 v[64:65], v[64:65], v[92:93]
	v_min_f32_e32 v33, v33, v41
	v_lshl_add_u32 v34, v85, 3, 0
	v_cndmask_b32_e64 v49, v49, v102, s[38:39]
	v_cndmask_b32_e64 v85, v132, v68, s[38:39]
	v_pk_add_f32 v[64:65], v[64:65], v[68:69]
	v_rcp_f32_e32 v68, v33
	v_or_b32_e32 v33, 1, v82
	v_cndmask_b32_e64 v50, v49, v50, s[34:35]
	v_add_u32_e32 v49, s10, v33
	v_pk_add_f32 v[134:135], v[122:123], v[106:107]
	v_cvt_f32_i32_e32 v49, v49
	v_pk_add_f32 v[126:127], v[28:29], v[24:25]
	v_pk_add_f32 v[146:147], v[118:119], v[134:135]
	v_pk_add_f32 v[118:119], v[110:111], v[118:119]
	v_pk_add_f32 v[110:111], v[98:99], v[110:111]
	v_pk_add_f32 v[98:99], v[90:91], v[98:99]
	v_pk_add_f32 v[90:91], v[78:79], v[90:91]
	v_pk_add_f32 v[62:63], v[62:63], v[70:71]
	v_pk_add_f32 v[56:57], v[134:135], v[126:127]
	v_pk_add_f32 v[78:79], v[70:71], v[78:79]
	v_cndmask_b32_e64 v135, v147, v135, s[36:37]
	v_cndmask_b32_e64 v134, v146, v134, s[36:37]
	v_pk_add_f32 v[70:71], v[110:111], v[146:147]
	v_pk_add_f32 v[62:63], v[62:63], v[90:91]
	v_cndmask_b32_e64 v87, v134, v70, s[38:39]
	v_cndmask_b32_e64 v88, v135, v71, s[38:39]
	v_pk_add_f32 v[62:63], v[62:63], v[70:71]
	v_xor_b32_e32 v71, 0x80000000, v125
	v_xor_b32_e32 v70, 0x80000000, v124
	v_pk_fma_f32 v[52:53], v[68:69], v[52:53], v[70:71] op_sel_hi:[0,1,1]
	v_pk_fma_f32 v[50:51], v[68:69], v[50:51], v[122:123] op_sel_hi:[0,1,1] neg_lo:[0,0,1] neg_hi:[0,0,1]
	v_min_f32_e32 v49, v49, v41
	v_cvt_pk_bf16_f32 v50, v50, v51
	v_cvt_pk_bf16_f32 v51, v52, v53
	v_rcp_f32_e32 v52, v49
	v_add_u32_e32 v49, 2, v42
	v_cvt_f32_i32_e32 v49, v49
	v_cndmask_b32_e64 v133, v145, v133, s[36:37]
	s_movk_i32 s10, 0x840
	v_cndmask_b32_e64 v86, v133, v69, s[38:39]
	v_mad_u64_u32 v[68:69], s[10:11], v83, s10, v[34:35]
	v_cndmask_b32_e64 v65, v86, v65, s[34:35]
	v_cndmask_b32_e64 v64, v85, v64, s[34:35]
	v_cndmask_b32_e64 v63, v88, v63, s[34:35]
	v_cndmask_b32_e64 v62, v87, v62, s[34:35]
	ds_write_b64 v68, v[50:51] offset:48128
	v_xor_b32_e32 v51, 0x80000000, v109
	v_xor_b32_e32 v50, 0x80000000, v108
	v_pk_add_f32 v[128:129], v[108:109], v[30:31]
	v_pk_add_f32 v[130:131], v[106:107], v[28:29]
	v_pk_fma_f32 v[50:51], v[52:53], v[64:65], v[50:51] op_sel_hi:[0,1,1]
	v_pk_fma_f32 v[52:53], v[52:53], v[62:63], v[106:107] op_sel_hi:[0,1,1] neg_lo:[0,0,1] neg_hi:[0,0,1]
	v_mad_u64_u32 v[62:63], s[10:11], v33, s72, v[34:35]
	v_min_f32_e32 v33, v49, v41
	v_pk_add_f32 v[140:141], v[136:137], v[128:129]
	v_pk_add_f32 v[142:143], v[138:139], v[130:131]
	v_pk_add_f32 v[74:75], v[66:67], v[74:75]
	v_cvt_pk_bf16_f32 v52, v52, v53
	v_cvt_pk_bf16_f32 v53, v50, v51
	v_rcp_f32_e32 v50, v33
	v_add_u32_e32 v33, 3, v42
	v_cndmask_b32_e64 v129, v141, v129, s[36:37]
	v_cndmask_b32_e64 v128, v140, v128, s[36:37]
	v_cndmask_b32_e64 v131, v143, v131, s[36:37]
	v_cndmask_b32_e64 v130, v142, v130, s[36:37]
	v_cndmask_b32_e64 v136, v55, v59, s[36:37]
	v_cndmask_b32_e64 v137, v54, v58, s[36:37]
	v_pk_add_f32 v[58:59], v[116:117], v[140:141]
	v_pk_add_f32 v[66:67], v[114:115], v[142:143]
	v_pk_add_f32 v[76:77], v[76:77], v[96:97]
	v_pk_add_f32 v[74:75], v[74:75], v[94:95]
	v_cvt_f32_i32_e32 v33, v33
	v_cndmask_b32_e64 v89, v128, v58, s[38:39]
	v_cndmask_b32_e64 v90, v129, v59, s[38:39]
	v_cndmask_b32_e64 v91, v130, v66, s[38:39]
	v_cndmask_b32_e64 v92, v131, v67, s[38:39]
	v_pk_add_f32 v[58:59], v[76:77], v[58:59]
	v_pk_add_f32 v[66:67], v[74:75], v[66:67]
	v_cndmask_b32_e64 v59, v90, v59, s[34:35]
	v_cndmask_b32_e64 v58, v89, v58, s[34:35]
	v_cndmask_b32_e64 v67, v92, v67, s[34:35]
	v_cndmask_b32_e64 v66, v91, v66, s[34:35]
	v_xor_b32_e32 v31, 0x80000000, v31
	v_xor_b32_e32 v30, 0x80000000, v30
	v_pk_fma_f32 v[30:31], v[50:51], v[58:59], v[30:31] op_sel_hi:[0,1,1]
	v_pk_fma_f32 v[28:29], v[50:51], v[66:67], v[28:29] op_sel_hi:[0,1,1] neg_lo:[0,0,1] neg_hi:[0,0,1]
	ds_write_b64 v62, v[52:53] offset:48128
	v_cvt_pk_bf16_f32 v28, v28, v29
	v_cvt_pk_bf16_f32 v29, v30, v31
	v_min_f32_e32 v30, v33, v41
	v_rcp_f32_e32 v30, v30
	v_cndmask_b32_e64 v127, v57, v127, s[36:37]
	v_cndmask_b32_e64 v126, v56, v126, s[36:37]
	v_pk_add_f32 v[56:57], v[118:119], v[56:57]
	v_pk_add_f32 v[78:79], v[78:79], v[98:99]
	v_pk_add_f32 v[54:55], v[120:121], v[54:55]
	v_pk_add_f32 v[80:81], v[80:81], v[100:101]
	v_cndmask_b32_e64 v95, v126, v56, s[38:39]
	v_cndmask_b32_e64 v96, v127, v57, s[38:39]
	v_pk_add_f32 v[56:57], v[78:79], v[56:57]
	v_cndmask_b32_e64 v93, v137, v54, s[38:39]
	v_cndmask_b32_e64 v94, v136, v55, s[38:39]
	v_pk_add_f32 v[54:55], v[80:81], v[54:55]
	v_cndmask_b32_e64 v57, v96, v57, s[34:35]
	v_cndmask_b32_e64 v56, v95, v56, s[34:35]
	v_cndmask_b32_e64 v55, v94, v55, s[34:35]
	v_cndmask_b32_e64 v54, v93, v54, s[34:35]
	v_xor_b32_e32 v27, 0x80000000, v27
	v_xor_b32_e32 v26, 0x80000000, v26
	v_pk_fma_f32 v[24:25], v[30:31], v[56:57], v[24:25] op_sel_hi:[0,1,1] neg_lo:[0,0,1] neg_hi:[0,0,1]
	ds_write_b64 v62, v[28:29] offset:48656
	v_pk_fma_f32 v[26:27], v[30:31], v[54:55], v[26:27] op_sel_hi:[0,1,1]
	v_cvt_pk_bf16_f32 v24, v24, v25
	v_cvt_pk_bf16_f32 v25, v26, v27
	ds_write_b64 v62, v[24:25] offset:49184
	s_waitcnt lgkmcnt(0)
	s_barrier
	s_and_saveexec_b64 s[10:11], s[22:23]
	s_cbranch_execnz .LBB0_764
	s_or_b64 exec, exec, s[10:11]
	s_and_saveexec_b64 s[10:11], s[24:25]
	s_cbranch_execnz .LBB0_765

.LBB0_686:
	s_or_b64 exec, exec, s[10:11]
	s_or_b32 s12, s4, 49
	v_add_u32_e32 v1, s12, v83
	v_cmp_lt_i32_e64 s[40:41], -1, v1
	s_and_b64 s[16:17], s[22:23], s[40:41]
	v_mov_b32_e32 v0, 0
	v_mov_b32_e32 v4, 0
	v_mov_b32_e32 v5, 0
	v_mov_b32_e32 v6, 0
	v_mov_b32_e32 v7, 0
	s_waitcnt lgkmcnt(0)
	s_barrier
	v_mov_b32_e32 v184, 0
	v_mov_b32_e32 v185, 0
	v_mov_b32_e32 v186, 0
	v_mov_b32_e32 v187, 0
	v_mov_b32_e32 v188, 0
	v_mov_b32_e32 v189, 0
	v_mov_b32_e32 v190, 0
	v_mov_b32_e32 v191, 0
	v_mov_b32_e32 v192, 0
	v_mov_b32_e32 v193, 0
	v_mov_b32_e32 v194, 0
	v_mov_b32_e32 v195, 0
	s_and_saveexec_b64 s[10:11], s[16:17]
	s_cbranch_execz .LBB0_688
	v_add_u32_e32 v1, s50, v1
	v_mov_b64_e32 v[2:3], s[48:49]
	v_mad_u64_u32 v[2:3], s[16:17], v1, s18, v[2:3]
	v_mov_b32_e32 v33, v175
	v_lshl_add_u64 v[2:3], v[2:3], 0, v[32:33]
	global_load_dwordx2 v[184:185], v[2:3], off offset:1024
.LBB0_688:
	s_or_b64 exec, exec, s[10:11]
	v_add_u32_e32 v8, s12, v44
	v_cmp_lt_i32_e64 s[40:41], -1, v8
	s_and_b64 s[16:17], s[24:25], s[40:41]
	v_mov_b32_e32 v1, 0
	v_mov_b32_e32 v2, 0
	v_mov_b32_e32 v3, 0
	s_and_saveexec_b64 s[10:11], s[16:17]
	s_cbranch_execz .LBB0_690
	v_add_u32_e32 v2, s50, v8
	v_mov_b64_e32 v[0:1], s[48:49]
	v_mad_u64_u32 v[0:1], s[16:17], v2, s18, v[0:1]
	v_mov_b32_e32 v33, v175
	v_lshl_add_u64 v[0:1], v[0:1], 0, v[32:33]
	global_load_dwordx2 v[186:187], v[0:1], off offset:1024
.LBB0_690:
	s_or_b64 exec, exec, s[10:11]
	v_add_u32_e32 v9, s12, v45
	v_cmp_lt_i32_e64 s[40:41], -1, v9
	s_and_b64 s[16:17], s[26:27], s[40:41]
	v_mov_b32_e32 v8, 0
	v_mov_b32_e32 v12, 0
	v_mov_b32_e32 v13, 0
	v_mov_b32_e32 v14, 0
	v_mov_b32_e32 v15, 0
	s_and_saveexec_b64 s[10:11], s[16:17]
	s_cbranch_execz .LBB0_692
	v_add_u32_e32 v9, s50, v9
	v_mov_b64_e32 v[10:11], s[48:49]
	v_mad_u64_u32 v[10:11], s[16:17], v9, s18, v[10:11]
	v_mov_b32_e32 v33, v175
	v_lshl_add_u64 v[10:11], v[10:11], 0, v[32:33]
	global_load_dwordx2 v[188:189], v[10:11], off offset:1024
.LBB0_692:
	s_or_b64 exec, exec, s[10:11]
	v_add_u32_e32 v16, s12, v46
	v_cmp_lt_i32_e64 s[40:41], -1, v16
	s_and_b64 s[16:17], s[28:29], s[40:41]
	v_mov_b32_e32 v9, 0
	v_mov_b32_e32 v10, 0
	v_mov_b32_e32 v11, 0
	s_and_saveexec_b64 s[10:11], s[16:17]
	s_cbranch_execz .LBB0_694
	v_add_u32_e32 v10, s50, v16
	v_mov_b64_e32 v[8:9], s[48:49]
	v_mad_u64_u32 v[8:9], s[16:17], v10, s18, v[8:9]
	v_mov_b32_e32 v33, v175
	v_lshl_add_u64 v[8:9], v[8:9], 0, v[32:33]
	global_load_dwordx2 v[190:191], v[8:9], off offset:1024
.LBB0_694:
	s_or_b64 exec, exec, s[10:11]
	v_add_u32_e32 v17, s12, v47
	v_cmp_lt_i32_e64 s[40:41], -1, v17
	s_and_b64 s[16:17], vcc, s[40:41]
	v_mov_b32_e32 v16, 0
	v_mov_b32_e32 v20, 0
	v_mov_b32_e32 v21, 0
	v_mov_b32_e32 v22, 0
	v_mov_b32_e32 v23, 0
	s_and_saveexec_b64 s[10:11], s[16:17]
	s_cbranch_execz .LBB0_696
	v_add_u32_e32 v17, s50, v17
	v_mov_b64_e32 v[18:19], s[48:49]
	v_mad_u64_u32 v[18:19], s[16:17], v17, s18, v[18:19]
	v_mov_b32_e32 v33, v175
	v_lshl_add_u64 v[18:19], v[18:19], 0, v[32:33]
	global_load_dwordx2 v[192:193], v[18:19], off offset:1024
.LBB0_696:
	s_or_b64 exec, exec, s[10:11]
	v_add_u32_e32 v24, s12, v48
	v_cmp_lt_i32_e64 s[40:41], -1, v24
	s_and_b64 s[12:13], s[30:31], s[40:41]
	v_mov_b32_e32 v17, 0
	v_mov_b32_e32 v18, 0
	v_mov_b32_e32 v19, 0
	s_and_saveexec_b64 s[10:11], s[12:13]
	s_cbranch_execz .LBB0_698
	v_add_u32_e32 v18, s50, v24
	v_mov_b64_e32 v[16:17], s[48:49]
	v_mad_u64_u32 v[16:17], s[12:13], v18, s18, v[16:17]
	v_mov_b32_e32 v33, v175
	v_lshl_add_u64 v[16:17], v[16:17], 0, v[32:33]
	global_load_dwordx2 v[194:195], v[16:17], off offset:1024
.LBB0_698:
	s_or_b64 exec, exec, s[10:11]
	s_waitcnt vmcnt(0)
	v_lshlrev_b32_e32 v4, 16, v184
	v_and_b32_e32 v5, 0xffff0000, v184
	v_lshlrev_b32_e32 v6, 16, v185
	v_and_b32_e32 v7, 0xffff0000, v185
	v_lshlrev_b32_e32 v0, 16, v186
	v_and_b32_e32 v1, 0xffff0000, v186
	v_lshlrev_b32_e32 v2, 16, v187
	v_and_b32_e32 v3, 0xffff0000, v187
	v_lshlrev_b32_e32 v12, 16, v188
	v_and_b32_e32 v13, 0xffff0000, v188
	v_lshlrev_b32_e32 v14, 16, v189
	v_and_b32_e32 v15, 0xffff0000, v189
	v_lshlrev_b32_e32 v8, 16, v190
	v_and_b32_e32 v9, 0xffff0000, v190
	v_lshlrev_b32_e32 v10, 16, v191
	v_and_b32_e32 v11, 0xffff0000, v191
	v_lshlrev_b32_e32 v20, 16, v192
	v_and_b32_e32 v21, 0xffff0000, v192
	v_lshlrev_b32_e32 v22, 16, v193
	v_and_b32_e32 v23, 0xffff0000, v193
	v_lshlrev_b32_e32 v16, 16, v194
	v_and_b32_e32 v17, 0xffff0000, v194
	v_lshlrev_b32_e32 v18, 16, v195
	v_and_b32_e32 v19, 0xffff0000, v195
	ds_read_b128 v[50:53], v43
	ds_read_b128 v[54:57], v43 offset:1024
	ds_read_b128 v[62:65], v43 offset:2048
	ds_read_b128 v[66:69], v43 offset:3072
	ds_read_b128 v[70:73], v43 offset:4096
	ds_read_b128 v[74:77], v43 offset:5120
	ds_read_b128 v[78:81], v43 offset:6144
	ds_read_b128 v[84:87], v43 offset:7168
	ds_read_b128 v[88:91], v43 offset:8192
	ds_read_b128 v[92:95], v43 offset:9216
	ds_read_b128 v[96:99], v43 offset:10240
	ds_read_b128 v[100:103], v43 offset:11264
	ds_read_b128 v[104:107], v43 offset:16384
	ds_read_b128 v[28:31], v43 offset:17408
	ds_read_b128 v[24:27], v43 offset:18432
	ds_read_b128 v[108:111], v43 offset:12288
	ds_read_b128 v[112:115], v43 offset:13312
	ds_read_b128 v[116:119], v43 offset:14336
	ds_read_b128 v[120:123], v43 offset:15360
	s_waitcnt lgkmcnt(14)
	v_pk_add_f32 v[52:53], v[52:53], v[56:57]
	s_waitcnt lgkmcnt(4)
	v_pk_add_f32 v[58:59], v[30:31], v[26:27]
	v_pk_add_f32 v[50:51], v[50:51], v[54:55]
	v_pk_add_f32 v[126:127], v[106:107], v[30:31]
	s_waitcnt lgkmcnt(0)
	v_pk_add_f32 v[134:135], v[118:119], v[122:123]
	v_pk_add_f32 v[118:119], v[114:115], v[118:119]
	v_pk_add_f32 v[114:115], v[110:111], v[114:115]
	v_pk_add_f32 v[110:111], v[102:103], v[110:111]
	v_pk_add_f32 v[102:103], v[98:99], v[102:103]
	v_pk_add_f32 v[98:99], v[94:95], v[98:99]
	v_pk_add_f32 v[94:95], v[90:91], v[94:95]
	v_pk_add_f32 v[90:91], v[86:87], v[90:91]
	v_pk_add_f32 v[86:87], v[80:81], v[86:87]
	v_pk_add_f32 v[80:81], v[76:77], v[80:81]
	v_pk_add_f32 v[76:77], v[72:73], v[76:77]
	v_pk_add_f32 v[72:73], v[68:69], v[72:73]
	v_pk_add_f32 v[68:69], v[64:65], v[68:69]
	v_pk_add_f32 v[130:131], v[122:123], v[106:107]
	v_pk_add_f32 v[64:65], v[56:57], v[64:65]
	v_pk_add_f32 v[146:147], v[114:115], v[134:135]
	v_pk_add_f32 v[114:115], v[102:103], v[114:115]
	v_pk_add_f32 v[102:103], v[94:95], v[102:103]
	v_pk_add_f32 v[94:95], v[86:87], v[94:95]
	v_pk_add_f32 v[86:87], v[76:77], v[86:87]
	v_pk_add_f32 v[52:53], v[52:53], v[68:69]
	v_pk_add_f32 v[142:143], v[118:119], v[130:131]
	v_pk_add_f32 v[118:119], v[110:111], v[118:119]
	v_pk_add_f32 v[110:111], v[98:99], v[110:111]
	v_pk_add_f32 v[98:99], v[90:91], v[98:99]
	v_pk_add_f32 v[90:91], v[80:81], v[90:91]
	v_pk_add_f32 v[80:81], v[72:73], v[80:81]
	v_pk_add_f32 v[64:65], v[64:65], v[72:73]
	v_cndmask_b32_e64 v33, v147, v135, s[36:37]
	v_pk_add_f32 v[72:73], v[102:103], v[146:147]
	v_pk_add_f32 v[52:53], v[52:53], v[86:87]
	v_cndmask_b32_e64 v33, v33, v73, s[38:39]
	v_pk_add_f32 v[52:53], v[52:53], v[72:73]
	v_pk_add_f32 v[136:137], v[116:117], v[120:121]
	v_cndmask_b32_e64 v53, v33, v53, s[34:35]
	v_add_u32_e32 v33, 32, v42
	v_cvt_f32_i32_e32 v33, v33
	v_pk_add_f32 v[116:117], v[112:113], v[116:117]
	v_pk_add_f32 v[112:113], v[108:109], v[112:113]
	v_pk_add_f32 v[108:109], v[100:101], v[108:109]
	v_pk_add_f32 v[100:101], v[96:97], v[100:101]
	v_pk_add_f32 v[96:97], v[92:93], v[96:97]
	v_pk_add_f32 v[92:93], v[88:89], v[92:93]
	v_pk_add_f32 v[88:89], v[84:85], v[88:89]
	v_pk_add_f32 v[84:85], v[78:79], v[84:85]
	v_pk_add_f32 v[78:79], v[74:75], v[78:79]
	v_pk_add_f32 v[74:75], v[70:71], v[74:75]
	v_pk_add_f32 v[70:71], v[66:67], v[70:71]
	v_pk_add_f32 v[66:67], v[62:63], v[66:67]
	v_pk_add_f32 v[62:63], v[54:55], v[62:63]
	v_pk_add_f32 v[54:55], v[130:131], v[58:59]
	v_pk_add_f32 v[76:77], v[68:69], v[76:77]
	v_cndmask_b32_e64 v130, v142, v130, s[36:37]
	v_pk_add_f32 v[68:69], v[110:111], v[142:143]
	v_pk_add_f32 v[64:65], v[64:65], v[90:91]
	v_min_f32_e32 v33, v33, v41
	v_cndmask_b32_e64 v86, v130, v68, s[38:39]
	v_pk_add_f32 v[64:65], v[64:65], v[68:69]
	v_rcp_f32_e32 v68, v33
	v_add_u32_e32 v33, 33, v42
	v_cvt_f32_i32_e32 v33, v33
	v_pk_add_f32 v[132:133], v[120:121], v[104:105]
	v_pk_add_f32 v[148:149], v[112:113], v[136:137]
	v_pk_add_f32 v[112:113], v[100:101], v[112:113]
	v_pk_add_f32 v[100:101], v[92:93], v[100:101]
	v_pk_add_f32 v[92:93], v[84:85], v[92:93]
	v_pk_add_f32 v[84:85], v[74:75], v[84:85]
	v_pk_add_f32 v[50:51], v[50:51], v[66:67]
	v_pk_add_f32 v[124:125], v[28:29], v[24:25]
	v_pk_add_f32 v[138:139], v[134:135], v[126:127]
	v_pk_add_f32 v[144:145], v[116:117], v[132:133]
	v_pk_add_f32 v[116:117], v[108:109], v[116:117]
	v_pk_add_f32 v[108:109], v[96:97], v[108:109]
	v_pk_add_f32 v[96:97], v[88:89], v[96:97]
	v_pk_add_f32 v[88:89], v[78:79], v[88:89]
	v_pk_add_f32 v[62:63], v[62:63], v[70:71]
	v_cndmask_b32_e64 v49, v146, v134, s[36:37]
	v_cndmask_b32_e64 v134, v149, v137, s[36:37]
	v_cndmask_b32_e64 v135, v148, v136, s[36:37]
	v_pk_add_f32 v[100:101], v[100:101], v[148:149]
	v_pk_add_f32 v[50:51], v[50:51], v[84:85]
	v_pk_add_f32 v[56:57], v[132:133], v[124:125]
	v_pk_add_f32 v[78:79], v[70:71], v[78:79]
	v_cndmask_b32_e64 v133, v145, v133, s[36:37]
	v_cndmask_b32_e64 v132, v144, v132, s[36:37]
	v_pk_add_f32 v[70:71], v[108:109], v[144:145]
	v_pk_add_f32 v[62:63], v[62:63], v[88:89]
	v_cndmask_b32_e64 v49, v49, v72, s[38:39]
	v_cndmask_b32_e64 v84, v135, v100, s[38:39]
	v_cndmask_b32_e64 v85, v134, v101, s[38:39]
	v_pk_add_f32 v[50:51], v[50:51], v[100:101]
	v_cndmask_b32_e64 v88, v132, v70, s[38:39]
	v_cndmask_b32_e64 v89, v133, v71, s[38:39]
	v_pk_add_f32 v[62:63], v[62:63], v[70:71]
	v_cndmask_b32_e64 v52, v49, v52, s[34:35]
	v_cndmask_b32_e64 v51, v85, v51, s[34:35]
	v_cndmask_b32_e64 v50, v84, v50, s[34:35]
	v_xor_b32_e32 v71, 0x80000000, v123
	v_xor_b32_e32 v70, 0x80000000, v122
	v_min_f32_e32 v33, v33, v41
	v_pk_fma_f32 v[52:53], v[68:69], v[52:53], v[70:71] op_sel_hi:[0,1,1]
	v_pk_fma_f32 v[50:51], v[68:69], v[50:51], v[120:121] op_sel_hi:[0,1,1] neg_lo:[0,0,1] neg_hi:[0,0,1]
	v_rcp_f32_e32 v68, v33
	v_add_u32_e32 v33, 34, v42
	v_cvt_f32_i32_e32 v33, v33
	v_cndmask_b32_e64 v131, v143, v131, s[36:37]
	v_cndmask_b32_e64 v87, v131, v69, s[38:39]
	v_cvt_pk_bf16_f32 v50, v50, v51
	v_cvt_pk_bf16_f32 v51, v52, v53
	v_mad_u64_u32 v[52:53], s[10:11], v82, s72, v[34:35]
	v_cndmask_b32_e64 v65, v87, v65, s[34:35]
	v_cndmask_b32_e64 v64, v86, v64, s[34:35]
	ds_write_b64 v52, v[50:51] offset:65024
	v_xor_b32_e32 v51, 0x80000000, v107
	v_xor_b32_e32 v50, 0x80000000, v106
	v_pk_add_f32 v[128:129], v[104:105], v[28:29]
	v_cndmask_b32_e64 v63, v89, v63, s[34:35]
	v_cndmask_b32_e64 v62, v88, v62, s[34:35]
	v_pk_fma_f32 v[50:51], v[68:69], v[64:65], v[50:51] op_sel_hi:[0,1,1]
	v_min_f32_e32 v33, v33, v41
	v_pk_add_f32 v[140:141], v[136:137], v[128:129]
	v_pk_add_f32 v[74:75], v[66:67], v[74:75]
	v_pk_fma_f32 v[62:63], v[68:69], v[62:63], v[104:105] op_sel_hi:[0,1,1] neg_lo:[0,0,1] neg_hi:[0,0,1]
	v_add_u32_e32 v49, 0x4410, v52
	v_cvt_pk_bf16_f32 v52, v62, v63
	v_cvt_pk_bf16_f32 v53, v50, v51
	v_rcp_f32_e32 v50, v33
	v_add_u32_e32 v33, 35, v42
	v_cndmask_b32_e64 v127, v139, v127, s[36:37]
	v_cndmask_b32_e64 v126, v138, v126, s[36:37]
	v_cndmask_b32_e64 v129, v141, v129, s[36:37]
	v_cndmask_b32_e64 v128, v140, v128, s[36:37]
	v_cndmask_b32_e64 v136, v55, v59, s[36:37]
	v_cndmask_b32_e64 v137, v54, v58, s[36:37]
	v_pk_add_f32 v[58:59], v[114:115], v[138:139]
	v_pk_add_f32 v[66:67], v[112:113], v[140:141]
	v_pk_add_f32 v[76:77], v[76:77], v[94:95]
	v_pk_add_f32 v[74:75], v[74:75], v[92:93]
	v_cvt_f32_i32_e32 v33, v33
	v_cndmask_b32_e64 v90, v126, v58, s[38:39]
	v_cndmask_b32_e64 v91, v127, v59, s[38:39]
	v_cndmask_b32_e64 v92, v128, v66, s[38:39]
	v_cndmask_b32_e64 v93, v129, v67, s[38:39]
	v_pk_add_f32 v[58:59], v[76:77], v[58:59]
	v_pk_add_f32 v[66:67], v[74:75], v[66:67]
	v_cndmask_b32_e64 v59, v91, v59, s[34:35]
	v_cndmask_b32_e64 v58, v90, v58, s[34:35]
	v_cndmask_b32_e64 v67, v93, v67, s[34:35]
	v_cndmask_b32_e64 v66, v92, v66, s[34:35]
	v_xor_b32_e32 v31, 0x80000000, v31
	v_xor_b32_e32 v30, 0x80000000, v30
	v_pk_fma_f32 v[30:31], v[50:51], v[58:59], v[30:31] op_sel_hi:[0,1,1]
	v_pk_fma_f32 v[28:29], v[50:51], v[66:67], v[28:29] op_sel_hi:[0,1,1] neg_lo:[0,0,1] neg_hi:[0,0,1]
	ds_write_b64 v49, v[52:53] offset:48128
	v_cvt_pk_bf16_f32 v28, v28, v29
	v_cvt_pk_bf16_f32 v29, v30, v31
	v_min_f32_e32 v30, v33, v41
	v_rcp_f32_e32 v30, v30
	v_cndmask_b32_e64 v125, v57, v125, s[36:37]
	v_cndmask_b32_e64 v124, v56, v124, s[36:37]
	v_pk_add_f32 v[56:57], v[116:117], v[56:57]
	v_pk_add_f32 v[78:79], v[78:79], v[96:97]
	v_pk_add_f32 v[54:55], v[118:119], v[54:55]
	v_pk_add_f32 v[80:81], v[80:81], v[98:99]
	v_cndmask_b32_e64 v96, v124, v56, s[38:39]
	v_cndmask_b32_e64 v97, v125, v57, s[38:39]
	v_pk_add_f32 v[56:57], v[78:79], v[56:57]
	v_cndmask_b32_e64 v94, v137, v54, s[38:39]
	v_cndmask_b32_e64 v95, v136, v55, s[38:39]
	v_pk_add_f32 v[54:55], v[80:81], v[54:55]
	v_cndmask_b32_e64 v57, v97, v57, s[34:35]
	v_cndmask_b32_e64 v56, v96, v56, s[34:35]
	v_cndmask_b32_e64 v55, v95, v55, s[34:35]
	v_cndmask_b32_e64 v54, v94, v54, s[34:35]
	v_xor_b32_e32 v27, 0x80000000, v27
	v_xor_b32_e32 v26, 0x80000000, v26
	v_pk_fma_f32 v[24:25], v[30:31], v[56:57], v[24:25] op_sel_hi:[0,1,1] neg_lo:[0,0,1] neg_hi:[0,0,1]
	ds_write_b64 v49, v[28:29] offset:48656
	v_pk_fma_f32 v[26:27], v[30:31], v[54:55], v[26:27] op_sel_hi:[0,1,1]
	v_cvt_pk_bf16_f32 v24, v24, v25
	v_cvt_pk_bf16_f32 v25, v26, v27
	ds_write_b64 v49, v[24:25] offset:49184
	s_waitcnt lgkmcnt(0)
	s_barrier
	s_and_saveexec_b64 s[10:11], s[22:23]
	s_cbranch_execnz .LBB0_769
	s_or_b64 exec, exec, s[10:11]
	s_and_saveexec_b64 s[10:11], s[24:25]
	s_cbranch_execnz .LBB0_770

.LBB0_705:
	s_or_b64 exec, exec, s[10:11]
	s_or_b32 s4, s4, 0x51
	v_add_u32_e32 v1, s4, v83
	v_cmp_lt_i32_e64 s[40:41], -1, v1
	s_and_b64 s[12:13], s[22:23], s[40:41]
	v_mov_b32_e32 v0, 0
	v_mov_b32_e32 v4, 0
	v_mov_b32_e32 v5, 0
	v_mov_b32_e32 v6, 0
	v_mov_b32_e32 v7, 0
	s_waitcnt lgkmcnt(0)
	s_barrier
	v_mov_b32_e32 v184, 0
	v_mov_b32_e32 v185, 0
	v_mov_b32_e32 v186, 0
	v_mov_b32_e32 v187, 0
	v_mov_b32_e32 v188, 0
	v_mov_b32_e32 v189, 0
	v_mov_b32_e32 v190, 0
	v_mov_b32_e32 v191, 0
	v_mov_b32_e32 v192, 0
	v_mov_b32_e32 v193, 0
	v_mov_b32_e32 v194, 0
	v_mov_b32_e32 v195, 0
	s_and_saveexec_b64 s[10:11], s[12:13]
	s_cbranch_execz .LBB0_707
	v_add_u32_e32 v1, s50, v1
	v_mov_b64_e32 v[2:3], s[48:49]
	v_mad_u64_u32 v[2:3], s[12:13], v1, s18, v[2:3]
	v_mov_b32_e32 v33, v175
	v_lshl_add_u64 v[2:3], v[2:3], 0, v[32:33]
	global_load_dwordx2 v[184:185], v[2:3], off offset:1024
.LBB0_707:
	s_or_b64 exec, exec, s[10:11]
	v_add_u32_e32 v8, s4, v44
	v_cmp_lt_i32_e64 s[40:41], -1, v8
	s_and_b64 s[12:13], s[24:25], s[40:41]
	v_mov_b32_e32 v1, 0
	v_mov_b32_e32 v2, 0
	v_mov_b32_e32 v3, 0
	s_and_saveexec_b64 s[10:11], s[12:13]
	s_cbranch_execz .LBB0_709
	v_add_u32_e32 v2, s50, v8
	v_mov_b64_e32 v[0:1], s[48:49]
	v_mad_u64_u32 v[0:1], s[12:13], v2, s18, v[0:1]
	v_mov_b32_e32 v33, v175
	v_lshl_add_u64 v[0:1], v[0:1], 0, v[32:33]
	global_load_dwordx2 v[186:187], v[0:1], off offset:1024
.LBB0_709:
	s_or_b64 exec, exec, s[10:11]
	v_add_u32_e32 v9, s4, v45
	v_cmp_lt_i32_e64 s[40:41], -1, v9
	s_and_b64 s[12:13], s[26:27], s[40:41]
	v_mov_b32_e32 v8, 0
	v_mov_b32_e32 v12, 0
	v_mov_b32_e32 v13, 0
	v_mov_b32_e32 v14, 0
	v_mov_b32_e32 v15, 0
	s_and_saveexec_b64 s[10:11], s[12:13]
	s_cbranch_execz .LBB0_711
	v_add_u32_e32 v9, s50, v9
	v_mov_b64_e32 v[10:11], s[48:49]
	v_mad_u64_u32 v[10:11], s[12:13], v9, s18, v[10:11]
	v_mov_b32_e32 v33, v175
	v_lshl_add_u64 v[10:11], v[10:11], 0, v[32:33]
	global_load_dwordx2 v[188:189], v[10:11], off offset:1024
.LBB0_711:
	s_or_b64 exec, exec, s[10:11]
	v_add_u32_e32 v16, s4, v46
	v_cmp_lt_i32_e64 s[40:41], -1, v16
	s_and_b64 s[12:13], s[28:29], s[40:41]
	v_mov_b32_e32 v9, 0
	v_mov_b32_e32 v10, 0
	v_mov_b32_e32 v11, 0
	s_and_saveexec_b64 s[10:11], s[12:13]
	s_cbranch_execz .LBB0_713
	v_add_u32_e32 v10, s50, v16
	v_mov_b64_e32 v[8:9], s[48:49]
	v_mad_u64_u32 v[8:9], s[12:13], v10, s18, v[8:9]
	v_mov_b32_e32 v33, v175
	v_lshl_add_u64 v[8:9], v[8:9], 0, v[32:33]
	global_load_dwordx2 v[190:191], v[8:9], off offset:1024
.LBB0_713:
	s_or_b64 exec, exec, s[10:11]
	v_add_u32_e32 v17, s4, v47
	v_cmp_lt_i32_e64 s[40:41], -1, v17
	s_and_b64 s[12:13], vcc, s[40:41]
	v_mov_b32_e32 v16, 0
	v_mov_b32_e32 v20, 0
	v_mov_b32_e32 v21, 0
	v_mov_b32_e32 v22, 0
	v_mov_b32_e32 v23, 0
	s_and_saveexec_b64 s[10:11], s[12:13]
	s_cbranch_execz .LBB0_715
	v_add_u32_e32 v17, s50, v17
	v_mov_b64_e32 v[18:19], s[48:49]
	v_mad_u64_u32 v[18:19], s[12:13], v17, s18, v[18:19]
	v_mov_b32_e32 v33, v175
	v_lshl_add_u64 v[18:19], v[18:19], 0, v[32:33]
	global_load_dwordx2 v[192:193], v[18:19], off offset:1024
.LBB0_715:
	s_or_b64 exec, exec, s[10:11]
	v_add_u32_e32 v24, s4, v48
	v_cmp_lt_i32_e64 s[40:41], -1, v24
	s_and_b64 s[12:13], s[30:31], s[40:41]
	v_mov_b32_e32 v17, 0
	v_mov_b32_e32 v18, 0
	v_mov_b32_e32 v19, 0
	s_and_saveexec_b64 s[10:11], s[12:13]
	s_cbranch_execz .LBB0_717
	v_add_u32_e32 v18, s50, v24
	v_mov_b64_e32 v[16:17], s[48:49]
	v_mad_u64_u32 v[16:17], s[12:13], v18, s18, v[16:17]
	v_mov_b32_e32 v33, v175
	v_lshl_add_u64 v[16:17], v[16:17], 0, v[32:33]
	global_load_dwordx2 v[194:195], v[16:17], off offset:1024
.LBB0_717:
	s_or_b64 exec, exec, s[10:11]
	s_waitcnt vmcnt(0)
	v_lshlrev_b32_e32 v4, 16, v184
	v_and_b32_e32 v5, 0xffff0000, v184
	v_lshlrev_b32_e32 v6, 16, v185
	v_and_b32_e32 v7, 0xffff0000, v185
	v_lshlrev_b32_e32 v0, 16, v186
	v_and_b32_e32 v1, 0xffff0000, v186
	v_lshlrev_b32_e32 v2, 16, v187
	v_and_b32_e32 v3, 0xffff0000, v187
	v_lshlrev_b32_e32 v12, 16, v188
	v_and_b32_e32 v13, 0xffff0000, v188
	v_lshlrev_b32_e32 v14, 16, v189
	v_and_b32_e32 v15, 0xffff0000, v189
	v_lshlrev_b32_e32 v8, 16, v190
	v_and_b32_e32 v9, 0xffff0000, v190
	v_lshlrev_b32_e32 v10, 16, v191
	v_and_b32_e32 v11, 0xffff0000, v191
	v_lshlrev_b32_e32 v20, 16, v192
	v_and_b32_e32 v21, 0xffff0000, v192
	v_lshlrev_b32_e32 v22, 16, v193
	v_and_b32_e32 v23, 0xffff0000, v193
	v_lshlrev_b32_e32 v16, 16, v194
	v_and_b32_e32 v17, 0xffff0000, v194
	v_lshlrev_b32_e32 v18, 16, v195
	v_and_b32_e32 v19, 0xffff0000, v195
	ds_read_b128 v[44:47], v43
	ds_read_b128 v[48:51], v43 offset:1024
	ds_read_b128 v[52:55], v43 offset:2048
	ds_read_b128 v[56:59], v43 offset:3072
	ds_read_b128 v[62:65], v43 offset:4096
	ds_read_b128 v[66:69], v43 offset:5120
	ds_read_b128 v[70:73], v43 offset:6144
	ds_read_b128 v[74:77], v43 offset:7168
	ds_read_b128 v[78:81], v43 offset:8192
	ds_read_b128 v[84:87], v43 offset:9216
	ds_read_b128 v[88:91], v43 offset:10240
	ds_read_b128 v[92:95], v43 offset:11264
	ds_read_b128 v[96:99], v43 offset:16384
	ds_read_b128 v[28:31], v43 offset:17408
	ds_read_b128 v[24:27], v43 offset:18432
	ds_read_b128 v[100:103], v43 offset:12288
	ds_read_b128 v[104:107], v43 offset:13312
	ds_read_b128 v[108:111], v43 offset:14336
	ds_read_b128 v[112:115], v43 offset:15360
	s_waitcnt lgkmcnt(4)
	v_pk_add_f32 v[32:33], v[30:31], v[26:27]
	v_pk_add_f32 v[46:47], v[46:47], v[50:51]
	v_pk_add_f32 v[116:117], v[28:29], v[24:25]
	v_pk_add_f32 v[44:45], v[44:45], v[48:49]
	s_waitcnt lgkmcnt(0)
	v_pk_add_f32 v[122:123], v[114:115], v[98:99]
	v_pk_add_f32 v[126:127], v[110:111], v[114:115]
	v_pk_add_f32 v[110:111], v[106:107], v[110:111]
	v_pk_add_f32 v[106:107], v[102:103], v[106:107]
	v_pk_add_f32 v[102:103], v[94:95], v[102:103]
	v_pk_add_f32 v[94:95], v[90:91], v[94:95]
	v_pk_add_f32 v[90:91], v[86:87], v[90:91]
	v_pk_add_f32 v[86:87], v[80:81], v[86:87]
	v_pk_add_f32 v[80:81], v[76:77], v[80:81]
	v_pk_add_f32 v[76:77], v[72:73], v[76:77]
	v_pk_add_f32 v[72:73], v[68:69], v[72:73]
	v_pk_add_f32 v[68:69], v[64:65], v[68:69]
	v_pk_add_f32 v[64:65], v[58:59], v[64:65]
	v_pk_add_f32 v[58:59], v[54:55], v[58:59]
	v_pk_add_f32 v[54:55], v[50:51], v[54:55]
	v_pk_add_f32 v[124:125], v[112:113], v[96:97]
	v_pk_add_f32 v[128:129], v[108:109], v[112:113]
	v_pk_add_f32 v[108:109], v[104:105], v[108:109]
	v_pk_add_f32 v[104:105], v[100:101], v[104:105]
	v_pk_add_f32 v[100:101], v[92:93], v[100:101]
	v_pk_add_f32 v[92:93], v[88:89], v[92:93]
	v_pk_add_f32 v[88:89], v[84:85], v[88:89]
	v_pk_add_f32 v[84:85], v[78:79], v[84:85]
	v_pk_add_f32 v[78:79], v[74:75], v[78:79]
	v_pk_add_f32 v[74:75], v[70:71], v[74:75]
	v_pk_add_f32 v[70:71], v[66:67], v[70:71]
	v_pk_add_f32 v[66:67], v[62:63], v[66:67]
	v_pk_add_f32 v[62:63], v[56:57], v[62:63]
	v_pk_add_f32 v[56:57], v[52:53], v[56:57]
	v_pk_add_f32 v[52:53], v[48:49], v[52:53]
	v_pk_add_f32 v[134:135], v[110:111], v[122:123]
	v_pk_add_f32 v[110:111], v[102:103], v[110:111]
	v_pk_add_f32 v[102:103], v[90:91], v[102:103]
	v_pk_add_f32 v[90:91], v[80:81], v[90:91]
	v_pk_add_f32 v[80:81], v[72:73], v[80:81]
	v_pk_add_f32 v[54:55], v[54:55], v[64:65]
	v_pk_add_f32 v[48:49], v[122:123], v[32:33]
	v_pk_add_f32 v[136:137], v[108:109], v[124:125]
	v_pk_add_f32 v[138:139], v[106:107], v[126:127]
	v_pk_add_f32 v[108:109], v[100:101], v[108:109]
	v_pk_add_f32 v[106:107], v[94:95], v[106:107]
	v_pk_add_f32 v[100:101], v[88:89], v[100:101]
	v_pk_add_f32 v[94:95], v[86:87], v[94:95]
	v_pk_add_f32 v[88:89], v[78:79], v[88:89]
	v_pk_add_f32 v[86:87], v[76:77], v[86:87]
	v_pk_add_f32 v[78:79], v[70:71], v[78:79]
	v_pk_add_f32 v[76:77], v[68:69], v[76:77]
	v_pk_add_f32 v[68:69], v[58:59], v[68:69]
	v_pk_add_f32 v[52:53], v[52:53], v[62:63]
	v_pk_add_f32 v[46:47], v[46:47], v[58:59]
	v_cndmask_b32_e64 v122, v134, v122, s[36:37]
	v_pk_add_f32 v[58:59], v[102:103], v[134:135]
	v_pk_add_f32 v[54:55], v[54:55], v[80:81]
	v_pk_add_f32 v[50:51], v[124:125], v[116:117]
	v_pk_add_f32 v[70:71], v[62:63], v[70:71]
	v_cndmask_b32_e64 v124, v136, v124, s[36:37]
	v_pk_add_f32 v[62:63], v[100:101], v[136:137]
	v_pk_add_f32 v[52:53], v[52:53], v[78:79]
	v_cndmask_b32_e64 v78, v122, v58, s[38:39]
	v_pk_add_f32 v[54:55], v[54:55], v[58:59]
	v_add_u32_e32 v58, 64, v42
	v_cndmask_b32_e64 v80, v124, v62, s[38:39]
	v_pk_add_f32 v[52:53], v[52:53], v[62:63]
	v_cvt_f32_i32_e32 v62, v58
	v_pk_add_f32 v[118:119], v[98:99], v[30:31]
	v_pk_add_f32 v[120:121], v[96:97], v[28:29]
	v_pk_add_f32 v[140:141], v[104:105], v[128:129]
	v_pk_add_f32 v[72:73], v[64:65], v[72:73]
	v_pk_add_f32 v[130:131], v[126:127], v[118:119]
	v_pk_add_f32 v[132:133], v[128:129], v[120:121]
	v_cndmask_b32_e64 v83, v139, v127, s[36:37]
	v_cndmask_b32_e64 v127, v141, v129, s[36:37]
	v_cndmask_b32_e64 v129, v49, v33, s[36:37]
	v_cndmask_b32_e64 v142, v48, v32, s[36:37]
	v_pk_add_f32 v[32:33], v[110:111], v[48:49]
	v_pk_add_f32 v[72:73], v[72:73], v[90:91]
	v_pk_add_f32 v[70:71], v[70:71], v[88:89]
	v_pk_add_f32 v[68:69], v[68:69], v[86:87]
	v_cndmask_b32_e64 v87, v142, v32, s[38:39]
	v_cndmask_b32_e64 v88, v129, v33, s[38:39]
	v_pk_add_f32 v[32:33], v[72:73], v[32:33]
	v_pk_add_f32 v[104:105], v[92:93], v[104:105]
	v_cndmask_b32_e64 v58, v87, v32, s[34:35]
	v_min_f32_e32 v32, v62, v41
	v_rcp_f32_e32 v32, v32
	v_pk_add_f32 v[92:93], v[84:85], v[92:93]
	v_pk_add_f32 v[84:85], v[74:75], v[84:85]
	v_pk_add_f32 v[74:75], v[66:67], v[74:75]
	v_pk_add_f32 v[44:45], v[44:45], v[56:57]
	v_cndmask_b32_e64 v126, v138, v126, s[36:37]
	v_pk_add_f32 v[64:65], v[94:95], v[138:139]
	v_pk_add_f32 v[46:47], v[46:47], v[76:77]
	v_cndmask_b32_e64 v125, v137, v125, s[36:37]
	v_pk_add_f32 v[44:45], v[44:45], v[74:75]
	v_cndmask_b32_e64 v74, v126, v64, s[38:39]
	v_cndmask_b32_e64 v75, v83, v65, s[38:39]
	v_pk_add_f32 v[46:47], v[46:47], v[64:65]
	v_cndmask_b32_e64 v81, v125, v63, s[38:39]
	v_cndmask_b32_e64 v47, v75, v47, s[34:35]
	v_cndmask_b32_e64 v46, v74, v46, s[34:35]
	v_xor_b32_e32 v63, 0x80000000, v115
	v_xor_b32_e32 v62, 0x80000000, v114
	v_pk_fma_f32 v[46:47], v[32:33], v[46:47], v[62:63] op_sel_hi:[0,1,1]
	v_add_u32_e32 v62, 0x41, v42
	v_cndmask_b32_e64 v128, v140, v128, s[36:37]
	v_pk_add_f32 v[92:93], v[92:93], v[140:141]
	v_cvt_f32_i32_e32 v62, v62
	v_cndmask_b32_e64 v76, v128, v92, s[38:39]
	v_cndmask_b32_e64 v77, v127, v93, s[38:39]
	v_pk_add_f32 v[44:45], v[44:45], v[92:93]
	v_cndmask_b32_e64 v123, v135, v123, s[36:37]
	v_cndmask_b32_e64 v45, v77, v45, s[34:35]
	v_cndmask_b32_e64 v44, v76, v44, s[34:35]
	v_pk_fma_f32 v[44:45], v[32:33], v[44:45], v[112:113] op_sel_hi:[0,1,1] neg_lo:[0,0,1] neg_hi:[0,0,1]
	v_cvt_pk_bf16_f32 v44, v44, v45
	v_cvt_pk_bf16_f32 v45, v46, v47
	v_min_f32_e32 v46, v62, v41
	v_cndmask_b32_e64 v79, v123, v59, s[38:39]
	v_cndmask_b32_e64 v59, v88, v33, s[34:35]
	v_mul_lo_u32 v33, v82, s72
	v_rcp_f32_e32 v46, v46
	v_add_u32_e32 v32, 0x8400, v33
	v_add_u32_e32 v32, v34, v32
	v_cndmask_b32_e64 v55, v79, v55, s[34:35]
	v_cndmask_b32_e64 v54, v78, v54, s[34:35]
	v_cndmask_b32_e64 v53, v81, v53, s[34:35]
	v_cndmask_b32_e64 v52, v80, v52, s[34:35]
	ds_write_b64 v32, v[44:45] offset:48128
	v_xor_b32_e32 v45, 0x80000000, v99
	v_xor_b32_e32 v44, 0x80000000, v98
	v_pk_fma_f32 v[44:45], v[46:47], v[54:55], v[44:45] op_sel_hi:[0,1,1]
	v_pk_fma_f32 v[46:47], v[46:47], v[52:53], v[96:97] op_sel_hi:[0,1,1] neg_lo:[0,0,1] neg_hi:[0,0,1]
	v_add_u32_e32 v52, 0x42, v42
	v_cvt_f32_i32_e32 v52, v52
	s_mov_b32 s4, 0x8610
	v_add3_u32 v33, v33, v34, s4
	v_pk_add_f32 v[66:67], v[56:57], v[66:67]
	v_min_f32_e32 v34, v52, v41
	v_cvt_pk_bf16_f32 v46, v46, v47
	v_cvt_pk_bf16_f32 v47, v44, v45
	v_rcp_f32_e32 v34, v34
	v_add_u32_e32 v44, 0x43, v42
	v_cndmask_b32_e64 v119, v131, v119, s[36:37]
	v_cndmask_b32_e64 v118, v130, v118, s[36:37]
	v_cndmask_b32_e64 v121, v133, v121, s[36:37]
	v_cndmask_b32_e64 v120, v132, v120, s[36:37]
	v_cndmask_b32_e64 v117, v51, v117, s[36:37]
	v_cndmask_b32_e64 v116, v50, v116, s[36:37]
	v_pk_add_f32 v[48:49], v[108:109], v[50:51]
	v_pk_add_f32 v[50:51], v[106:107], v[130:131]
	v_pk_add_f32 v[56:57], v[104:105], v[132:133]
	v_pk_add_f32 v[66:67], v[66:67], v[84:85]
	v_cvt_f32_i32_e32 v44, v44
	v_cndmask_b32_e64 v83, v118, v50, s[38:39]
	v_cndmask_b32_e64 v84, v119, v51, s[38:39]
	v_cndmask_b32_e64 v85, v120, v56, s[38:39]
	v_cndmask_b32_e64 v86, v121, v57, s[38:39]
	v_pk_add_f32 v[50:51], v[68:69], v[50:51]
	v_pk_add_f32 v[56:57], v[66:67], v[56:57]
	v_cndmask_b32_e64 v51, v84, v51, s[34:35]
	v_cndmask_b32_e64 v50, v83, v50, s[34:35]
	v_cndmask_b32_e64 v57, v86, v57, s[34:35]
	v_cndmask_b32_e64 v56, v85, v56, s[34:35]
	v_xor_b32_e32 v31, 0x80000000, v31
	v_xor_b32_e32 v30, 0x80000000, v30
	v_pk_fma_f32 v[30:31], v[34:35], v[50:51], v[30:31] op_sel_hi:[0,1,1]
	v_pk_fma_f32 v[28:29], v[34:35], v[56:57], v[28:29] op_sel_hi:[0,1,1] neg_lo:[0,0,1] neg_hi:[0,0,1]
	ds_write_b64 v33, v[46:47] offset:48128
	v_cvt_pk_bf16_f32 v28, v28, v29
	v_cvt_pk_bf16_f32 v29, v30, v31
	v_min_f32_e32 v30, v44, v41
	v_rcp_f32_e32 v30, v30
	v_cndmask_b32_e64 v89, v116, v48, s[38:39]
	v_cndmask_b32_e64 v90, v117, v49, s[38:39]
	v_pk_add_f32 v[48:49], v[70:71], v[48:49]
	v_xor_b32_e32 v27, 0x80000000, v27
	v_cndmask_b32_e64 v49, v90, v49, s[34:35]
	v_cndmask_b32_e64 v48, v89, v48, s[34:35]
	v_xor_b32_e32 v26, 0x80000000, v26
	v_pk_fma_f32 v[24:25], v[30:31], v[48:49], v[24:25] op_sel_hi:[0,1,1] neg_lo:[0,0,1] neg_hi:[0,0,1]
	ds_write_b64 v33, v[28:29] offset:48656
	v_pk_fma_f32 v[26:27], v[30:31], v[58:59], v[26:27] op_sel_hi:[0,1,1]
	v_cvt_pk_bf16_f32 v24, v24, v25
	v_cvt_pk_bf16_f32 v25, v26, v27
	ds_write_b64 v33, v[24:25] offset:49184
	s_waitcnt lgkmcnt(0)
	s_barrier
	s_and_saveexec_b64 s[10:11], s[22:23]
	s_xor_b64 s[10:11], exec, s[10:11]
	s_cbranch_execnz .LBB0_774
	s_or_b64 exec, exec, s[10:11]
	s_and_saveexec_b64 s[10:11], s[24:25]
	s_cbranch_execnz .LBB0_775
